# 32x32x16 attention loop: last PV group of a tile deferred past the barrier (operands already in registers), hides the post-barrier K fragment latency
# baseline (speedup 1.0000x reference)
.Lattn_nf_loop:
	s_and_b32 s10, s15, 1
	s_mul_i32 s6, s10, 0x8800
	v_add_u32_e32 v136, s6, v137
	v_add_u32_e32 v170, s6, v183
	s_sub_u32 s10, 0x8800, s6
	ds_read_b128 v[98:101], v136 offset:0
	ds_read_b128 v[102:105], v136 offset:32
	ds_read_b128 v[106:109], v136 offset:64
	ds_read_b128 v[110:113], v136 offset:96
	v_add_u32_e32 v171, s10, v126
	v_add_u32_e32 v173, s10, v127
	global_load_dwordx4 v[82:85], v124, s[64:65]
	global_load_dwordx4 v[86:89], v124, s[66:67]
	global_load_dwordx4 v[90:93], v124, s[68:69]
	global_load_dwordx4 v[94:97], v124, s[70:71]
	v_add_u32_e32 v124, s36, v124
	s_cmp_eq_u32 s15, 0
	s_cbranch_scc1 .Lattn_nodefer
	v_mfma_f32_32x32x16_bf16 v[18:33], v[196:199], v[118:121], v[18:33]
	v_mfma_f32_32x32x16_bf16 v[34:49], v[216:219], v[118:121], v[34:49]
	v_mfma_f32_32x32x16_bf16 v[50:65], v[200:203], v[118:121], v[50:65]
	v_mfma_f32_32x32x16_bf16 v[66:81], v[204:207], v[118:121], v[66:81]
.Lattn_nodefer:
	s_waitcnt lgkmcnt(3)
	v_mfma_f32_32x32x16_bf16 v[138:153], v[98:101], v[10:13], 0
	ds_read_b128 v[98:101], v136 offset:8704
	s_waitcnt lgkmcnt(3)
	v_mfma_f32_32x32x16_bf16 v[138:153], v[102:105], v[14:17], v[138:153]
	ds_read_b128 v[102:105], v136 offset:8736
	s_waitcnt lgkmcnt(3)
	v_mfma_f32_32x32x16_bf16 v[138:153], v[106:109], v[2:5], v[138:153]
	ds_read_b128 v[106:109], v136 offset:8768
	s_waitcnt lgkmcnt(3)
	v_mfma_f32_32x32x16_bf16 v[138:153], v[110:113], v[6:9], v[138:153]
	ds_read_b128 v[110:113], v136 offset:8800
	ds_read_b128 v[128:131], v170 offset:0
	ds_read_b128 v[184:187], v170 offset:8704
	ds_read_b128 v[188:191], v170 offset:17408
	ds_read_b128 v[192:195], v170 offset:26112
	s_waitcnt lgkmcnt(7)
	v_mfma_f32_32x32x16_bf16 v[154:169], v[98:101], v[10:13], 0
	ds_read_b128 v[98:101], v136 offset:17408
	s_nop 3
	v_exp_f32_e32 v138, v138
	v_exp_f32_e32 v139, v139
	v_exp_f32_e32 v140, v140
	v_exp_f32_e32 v141, v141
	v_exp_f32_e32 v142, v142
	v_exp_f32_e32 v143, v143
	s_waitcnt lgkmcnt(7)
	v_mfma_f32_32x32x16_bf16 v[154:169], v[102:105], v[14:17], v[154:169]
	ds_read_b128 v[102:105], v136 offset:17440
	v_exp_f32_e32 v144, v144
	v_exp_f32_e32 v145, v145
	v_add_f32_e32 v122, v138, v122
	v_add_f32_e32 v122, v139, v122
	v_add_f32_e32 v122, v140, v122
	v_add_f32_e32 v122, v141, v122
	v_add_f32_e32 v122, v142, v122
	v_add_f32_e32 v122, v143, v122
	v_add_f32_e32 v122, v144, v122
	v_add_f32_e32 v122, v145, v122
	v_cvt_pk_bf16_f32 v114, v138, v139
	v_cvt_pk_bf16_f32 v115, v140, v141
	v_cvt_pk_bf16_f32 v116, v142, v143
	v_cvt_pk_bf16_f32 v117, v144, v145
	ds_read_b128 v[196:199], v170 offset:32
	ds_read_b128 v[216:219], v170 offset:8736
	ds_read_b128 v[200:203], v170 offset:17440
	ds_read_b128 v[204:207], v170 offset:26144
	s_waitcnt lgkmcnt(11)
	v_mfma_f32_32x32x16_bf16 v[154:169], v[106:109], v[2:5], v[154:169]
	ds_read_b128 v[106:109], v136 offset:17472
	v_exp_f32_e32 v146, v146
	v_exp_f32_e32 v147, v147
	s_waitcnt lgkmcnt(11)
	v_mfma_f32_32x32x16_bf16 v[154:169], v[110:113], v[6:9], v[154:169]
	ds_read_b128 v[110:113], v136 offset:17504
	v_exp_f32_e32 v148, v148
	v_exp_f32_e32 v149, v149
	s_waitcnt lgkmcnt(11)
	v_mfma_f32_32x32x16_bf16 v[18:33], v[128:131], v[114:117], v[18:33]
	v_exp_f32_e32 v150, v150
	v_exp_f32_e32 v151, v151
	s_waitcnt lgkmcnt(10)
	v_mfma_f32_32x32x16_bf16 v[34:49], v[184:187], v[114:117], v[34:49]
	v_exp_f32_e32 v152, v152
	v_exp_f32_e32 v153, v153
	s_waitcnt lgkmcnt(9)
	v_mfma_f32_32x32x16_bf16 v[50:65], v[188:191], v[114:117], v[50:65]
	v_add_f32_e32 v122, v146, v122
	v_add_f32_e32 v122, v147, v122
	v_add_f32_e32 v122, v148, v122
	v_add_f32_e32 v122, v149, v122
	s_waitcnt lgkmcnt(8)
	v_mfma_f32_32x32x16_bf16 v[66:81], v[192:195], v[114:117], v[66:81]
	v_add_f32_e32 v122, v150, v122
	v_add_f32_e32 v122, v151, v122
	v_add_f32_e32 v122, v152, v122
	v_add_f32_e32 v122, v153, v122
	v_cvt_pk_bf16_f32 v118, v146, v147
	v_cvt_pk_bf16_f32 v119, v148, v149
	v_cvt_pk_bf16_f32 v120, v150, v151
	v_cvt_pk_bf16_f32 v121, v152, v153
	ds_read_b128 v[128:131], v170 offset:64
	ds_read_b128 v[184:187], v170 offset:8768
	ds_read_b128 v[188:191], v170 offset:17472
	ds_read_b128 v[192:195], v170 offset:26176
	s_waitcnt lgkmcnt(11)
	v_mfma_f32_32x32x16_bf16 v[138:153], v[98:101], v[10:13], 0
	ds_read_b128 v[98:101], v136 offset:26112
	v_exp_f32_e32 v154, v154
	v_exp_f32_e32 v155, v155
	s_waitcnt lgkmcnt(11)
	v_mfma_f32_32x32x16_bf16 v[138:153], v[102:105], v[14:17], v[138:153]
	ds_read_b128 v[102:105], v136 offset:26144
	v_exp_f32_e32 v156, v156
	v_exp_f32_e32 v157, v157
	s_waitcnt lgkmcnt(11)
	v_mfma_f32_32x32x16_bf16 v[18:33], v[196:199], v[118:121], v[18:33]
	v_exp_f32_e32 v158, v158
	v_exp_f32_e32 v159, v159
	s_waitcnt lgkmcnt(10)
	v_mfma_f32_32x32x16_bf16 v[34:49], v[216:219], v[118:121], v[34:49]
	v_exp_f32_e32 v160, v160
	v_exp_f32_e32 v161, v161
	s_waitcnt lgkmcnt(9)
	v_mfma_f32_32x32x16_bf16 v[50:65], v[200:203], v[118:121], v[50:65]
	v_add_f32_e32 v122, v154, v122
	v_add_f32_e32 v122, v155, v122
	v_add_f32_e32 v122, v156, v122
	v_add_f32_e32 v122, v157, v122
	s_waitcnt lgkmcnt(8)
	v_mfma_f32_32x32x16_bf16 v[66:81], v[204:207], v[118:121], v[66:81]
	v_add_f32_e32 v122, v158, v122
	v_add_f32_e32 v122, v159, v122
	v_add_f32_e32 v122, v160, v122
	v_add_f32_e32 v122, v161, v122
	v_cvt_pk_bf16_f32 v114, v154, v155
	v_cvt_pk_bf16_f32 v115, v156, v157
	v_cvt_pk_bf16_f32 v116, v158, v159
	v_cvt_pk_bf16_f32 v117, v160, v161
	ds_read_b128 v[196:199], v170 offset:96
	ds_read_b128 v[216:219], v170 offset:8800
	ds_read_b128 v[200:203], v170 offset:17504
	ds_read_b128 v[204:207], v170 offset:26208
	s_waitcnt lgkmcnt(11)
	v_mfma_f32_32x32x16_bf16 v[138:153], v[106:109], v[2:5], v[138:153]
	ds_read_b128 v[106:109], v136 offset:26176
	v_exp_f32_e32 v162, v162
	v_exp_f32_e32 v163, v163
	s_waitcnt lgkmcnt(11)
	v_mfma_f32_32x32x16_bf16 v[138:153], v[110:113], v[6:9], v[138:153]
	ds_read_b128 v[110:113], v136 offset:26208
	v_exp_f32_e32 v164, v164
	v_exp_f32_e32 v165, v165
	s_waitcnt lgkmcnt(11)
	v_mfma_f32_32x32x16_bf16 v[18:33], v[128:131], v[114:117], v[18:33]
	v_exp_f32_e32 v166, v166
	v_exp_f32_e32 v167, v167
	s_waitcnt lgkmcnt(10)
	v_mfma_f32_32x32x16_bf16 v[34:49], v[184:187], v[114:117], v[34:49]
	v_exp_f32_e32 v168, v168
	v_exp_f32_e32 v169, v169
	s_waitcnt lgkmcnt(9)
	v_mfma_f32_32x32x16_bf16 v[50:65], v[188:191], v[114:117], v[50:65]
	v_add_f32_e32 v122, v162, v122
	v_add_f32_e32 v122, v163, v122
	v_add_f32_e32 v122, v164, v122
	v_add_f32_e32 v122, v165, v122
	s_waitcnt lgkmcnt(8)
	v_mfma_f32_32x32x16_bf16 v[66:81], v[192:195], v[114:117], v[66:81]
	v_add_f32_e32 v122, v166, v122
	v_add_f32_e32 v122, v167, v122
	v_add_f32_e32 v122, v168, v122
	v_add_f32_e32 v122, v169, v122
	v_cvt_pk_bf16_f32 v118, v162, v163
	v_cvt_pk_bf16_f32 v119, v164, v165
	v_cvt_pk_bf16_f32 v120, v166, v167
	v_cvt_pk_bf16_f32 v121, v168, v169
	ds_read_b128 v[128:131], v170 offset:128
	ds_read_b128 v[184:187], v170 offset:8832
	ds_read_b128 v[188:191], v170 offset:17536
	ds_read_b128 v[192:195], v170 offset:26240
	s_waitcnt lgkmcnt(11)
	v_mfma_f32_32x32x16_bf16 v[154:169], v[98:101], v[10:13], 0
	v_exp_f32_e32 v138, v138
	s_waitcnt lgkmcnt(10)
	v_mfma_f32_32x32x16_bf16 v[154:169], v[102:105], v[14:17], v[154:169]
	v_exp_f32_e32 v139, v139
	v_exp_f32_e32 v140, v140
	s_waitcnt lgkmcnt(9)
	v_mfma_f32_32x32x16_bf16 v[18:33], v[196:199], v[118:121], v[18:33]
	v_exp_f32_e32 v141, v141
	v_exp_f32_e32 v142, v142
	s_waitcnt vmcnt(3)
	ds_write_b128 v171, v[82:85] offset:0
	s_waitcnt vmcnt(2)
	ds_write_b128 v171, v[86:89] offset:8704
	s_waitcnt vmcnt(1)
	ds_write_b128 v171, v[90:93] offset:17408
	s_waitcnt vmcnt(0)
	ds_write_b128 v171, v[94:97] offset:26112
	v_exp_f32_e32 v143, v143
	s_waitcnt lgkmcnt(12)
	v_mfma_f32_32x32x16_bf16 v[34:49], v[216:219], v[118:121], v[34:49]
	v_exp_f32_e32 v144, v144
	v_exp_f32_e32 v145, v145
	v_add_f32_e32 v122, v138, v122
	s_waitcnt lgkmcnt(11)
	v_mfma_f32_32x32x16_bf16 v[50:65], v[200:203], v[118:121], v[50:65]
	v_add_f32_e32 v122, v139, v122
	v_add_f32_e32 v122, v140, v122
	v_add_f32_e32 v122, v141, v122
	s_waitcnt lgkmcnt(10)
	v_mfma_f32_32x32x16_bf16 v[66:81], v[204:207], v[118:121], v[66:81]
	v_add_f32_e32 v122, v142, v122
	v_add_f32_e32 v122, v143, v122
	v_add_f32_e32 v122, v144, v122
	v_add_f32_e32 v122, v145, v122
	v_cvt_pk_bf16_f32 v114, v138, v139
	v_cvt_pk_bf16_f32 v115, v140, v141
	v_cvt_pk_bf16_f32 v116, v142, v143
	v_cvt_pk_bf16_f32 v117, v144, v145
	ds_read_b128 v[196:199], v170 offset:160
	ds_read_b128 v[216:219], v170 offset:8864
	ds_read_b128 v[200:203], v170 offset:17568
	ds_read_b128 v[204:207], v170 offset:26272
	s_waitcnt lgkmcnt(13)
	v_mfma_f32_32x32x16_bf16 v[154:169], v[106:109], v[2:5], v[154:169]
	v_exp_f32_e32 v146, v146
	s_waitcnt lgkmcnt(12)
	v_mfma_f32_32x32x16_bf16 v[154:169], v[110:113], v[6:9], v[154:169]
	v_exp_f32_e32 v147, v147
	v_exp_f32_e32 v148, v148
	s_waitcnt lgkmcnt(11)
	v_mfma_f32_32x32x16_bf16 v[18:33], v[128:131], v[114:117], v[18:33]
	v_exp_f32_e32 v149, v149
	v_exp_f32_e32 v150, v150
	global_load_dwordx4 v[82:85], v125, s[72:73]
	global_load_dwordx4 v[86:89], v125, s[74:75]
	global_load_dwordx4 v[90:93], v125, s[76:77]
	global_load_dwordx4 v[94:97], v125, s[78:79]
	v_add_u32_e32 v125, s38, v125
	v_exp_f32_e32 v151, v151
	s_waitcnt lgkmcnt(10)
	v_mfma_f32_32x32x16_bf16 v[34:49], v[184:187], v[114:117], v[34:49]
	v_exp_f32_e32 v152, v152
	v_exp_f32_e32 v153, v153
	v_add_f32_e32 v122, v146, v122
	s_waitcnt lgkmcnt(9)
	v_mfma_f32_32x32x16_bf16 v[50:65], v[188:191], v[114:117], v[50:65]
	v_add_f32_e32 v122, v147, v122
	v_add_f32_e32 v122, v148, v122
	v_add_f32_e32 v122, v149, v122
	s_waitcnt lgkmcnt(8)
	v_mfma_f32_32x32x16_bf16 v[66:81], v[192:195], v[114:117], v[66:81]
	v_add_f32_e32 v122, v150, v122
	v_add_f32_e32 v122, v151, v122
	v_add_f32_e32 v122, v152, v122
	v_add_f32_e32 v122, v153, v122
	v_cvt_pk_bf16_f32 v118, v146, v147
	v_cvt_pk_bf16_f32 v119, v148, v149
	v_cvt_pk_bf16_f32 v120, v150, v151
	v_cvt_pk_bf16_f32 v121, v152, v153
	ds_read_b128 v[128:131], v170 offset:192
	ds_read_b128 v[184:187], v170 offset:8896
	ds_read_b128 v[188:191], v170 offset:17600
	ds_read_b128 v[192:195], v170 offset:26304
	s_waitcnt lgkmcnt(7)
	v_mfma_f32_32x32x16_bf16 v[18:33], v[196:199], v[118:121], v[18:33]
	v_exp_f32_e32 v154, v154
	v_exp_f32_e32 v155, v155
	v_exp_f32_e32 v156, v156
	s_waitcnt lgkmcnt(6)
	v_mfma_f32_32x32x16_bf16 v[34:49], v[216:219], v[118:121], v[34:49]
	v_exp_f32_e32 v157, v157
	v_exp_f32_e32 v158, v158
	v_exp_f32_e32 v159, v159
	s_waitcnt lgkmcnt(5)
	v_mfma_f32_32x32x16_bf16 v[50:65], v[200:203], v[118:121], v[50:65]
	v_exp_f32_e32 v160, v160
	v_exp_f32_e32 v161, v161
	v_add_f32_e32 v122, v154, v122
	v_add_f32_e32 v122, v155, v122
	s_waitcnt lgkmcnt(4)
	v_mfma_f32_32x32x16_bf16 v[66:81], v[204:207], v[118:121], v[66:81]
	v_add_f32_e32 v122, v156, v122
	v_add_f32_e32 v122, v157, v122
	v_add_f32_e32 v122, v158, v122
	v_add_f32_e32 v122, v159, v122
	v_add_f32_e32 v122, v160, v122
	v_add_f32_e32 v122, v161, v122
	v_cvt_pk_bf16_f32 v114, v154, v155
	v_cvt_pk_bf16_f32 v115, v156, v157
	v_cvt_pk_bf16_f32 v116, v158, v159
	v_cvt_pk_bf16_f32 v117, v160, v161
	ds_read_b128 v[196:199], v170 offset:224
	ds_read_b128 v[216:219], v170 offset:8928
	ds_read_b128 v[200:203], v170 offset:17632
	ds_read_b128 v[204:207], v170 offset:26336
	s_waitcnt lgkmcnt(7)
	v_mfma_f32_32x32x16_bf16 v[18:33], v[128:131], v[114:117], v[18:33]
	v_exp_f32_e32 v162, v162
	v_exp_f32_e32 v163, v163
	v_exp_f32_e32 v164, v164
	s_waitcnt lgkmcnt(6)
	v_mfma_f32_32x32x16_bf16 v[34:49], v[184:187], v[114:117], v[34:49]
	v_exp_f32_e32 v165, v165
	v_exp_f32_e32 v166, v166
	v_exp_f32_e32 v167, v167
	s_waitcnt lgkmcnt(5)
	v_mfma_f32_32x32x16_bf16 v[50:65], v[188:191], v[114:117], v[50:65]
	v_exp_f32_e32 v168, v168
	v_exp_f32_e32 v169, v169
	v_add_f32_e32 v122, v162, v122
	v_add_f32_e32 v122, v163, v122
	s_waitcnt lgkmcnt(4)
	v_mfma_f32_32x32x16_bf16 v[66:81], v[192:195], v[114:117], v[66:81]
	v_add_f32_e32 v122, v164, v122
	v_add_f32_e32 v122, v165, v122
	v_add_f32_e32 v122, v166, v122
	v_add_f32_e32 v122, v167, v122
	v_add_f32_e32 v122, v168, v122
	v_add_f32_e32 v122, v169, v122
	v_cvt_pk_bf16_f32 v118, v162, v163
	v_cvt_pk_bf16_f32 v119, v164, v165
	v_cvt_pk_bf16_f32 v120, v166, v167
	v_cvt_pk_bf16_f32 v121, v168, v169
	s_waitcnt vmcnt(3)
	ds_write_b128 v173, v[82:85] offset:0
	s_waitcnt vmcnt(2)
	ds_write_b128 v173, v[86:89] offset:8704
	s_waitcnt vmcnt(1)
	ds_write_b128 v173, v[90:93] offset:17408
	s_waitcnt vmcnt(0)
	ds_write_b128 v173, v[94:97] offset:26112
	s_waitcnt lgkmcnt(0)
	s_barrier
	s_add_i32 s15, s15, 1
	s_cmp_eq_u32 s15, 34
	s_cbranch_scc0 .Lattn_nf_loop
	v_mfma_f32_32x32x16_bf16 v[18:33], v[196:199], v[118:121], v[18:33]
	v_mfma_f32_32x32x16_bf16 v[34:49], v[216:219], v[118:121], v[34:49]
	v_mfma_f32_32x32x16_bf16 v[50:65], v[200:203], v[118:121], v[50:65]
	v_mfma_f32_32x32x16_bf16 v[66:81], v[204:207], v[118:121], v[66:81]
	v_readlane_b32 s64, v175, 0
	v_readlane_b32 s65, v175, 1
	v_readlane_b32 s66, v175, 2
	v_readlane_b32 s67, v175, 3
	v_readlane_b32 s68, v175, 4
	v_readlane_b32 s69, v175, 5
	v_readlane_b32 s70, v175, 6
	v_readlane_b32 s71, v175, 7
	v_readlane_b32 s72, v175, 8
	v_readlane_b32 s73, v175, 9
	v_readlane_b32 s74, v175, 10
	v_readlane_b32 s75, v175, 11
	v_readlane_b32 s76, v175, 12
	v_readlane_b32 s77, v175, 13
	v_readlane_b32 s78, v175, 14
	v_readlane_b32 s79, v175, 15
	s_nop 4
	v_add_f32_e32 v186, v132, v134
	v_add_f32_e32 v184, v133, v135
	ds_bpermute_b32 v187, v172, v186
	ds_bpermute_b32 v185, v172, v184
	s_mov_b32 s10, 0x3fb8aa3b
	s_mov_b32 s11, 0xc2ce8ed0
	s_mov_b32 s6, 0x42b17218
	v_cmp_eq_u32_e64 s[40:41], 0, v179
	s_lshl_b32 s30, s14, 1
	v_lshlrev_b32_e32 v196, 3, v178
	v_mov_b32_e32 v197, 0
	v_lshlrev_b32_e32 v198, 4, v179
	v_or3_b32 v198, v198, v177, v180
	v_ashrrev_i32_e32 v199, 31, v198
	v_lshlrev_b64 v[198:199], 11, v[198:199]
	s_mov_b64 s[100:101], 0x18a10000
	v_lshl_add_u64 v[198:199], s[42:43], 0, v[198:199]
	v_lshl_add_u64 v[198:199], v[198:199], 0, s[30:31]
	v_lshl_add_u64 v[198:199], v[198:199], 0, v[196:197]
	v_lshl_add_u64 v[198:199], v[198:199], 0, s[100:101]
	global_load_dwordx2 v[146:147], v[198:199], off
	global_load_dwordx2 v[148:149], v[198:199], off offset:32
	global_load_dwordx2 v[150:151], v[198:199], off offset:64
	global_load_dwordx2 v[152:153], v[198:199], off offset:96
	global_load_dwordx2 v[188:189], v[198:199], off offset:128
	global_load_dwordx2 v[190:191], v[198:199], off offset:160
	global_load_dwordx2 v[192:193], v[198:199], off offset:192
	global_load_dwordx2 v[194:195], v[198:199], off offset:224
	s_mov_b64 s[100:101], exec
	s_and_b64 exec, exec, s[4:5]
	s_cbranch_execz .Lpop_skip
	v_readlane_b32 s14, v255, 22
	v_readlane_b32 s15, v255, 23
	v_mov_b32_e32 v224, 1
	s_nop 4
	global_atomic_add v224, v0, v224, s[14:15] sc0
